# best stack; three-producer heads publish after every second round
# baseline (speedup 1.0000x reference)
; DEVINL void rw_project_head(const Ctx& c, int layer, int b, int hd, int pj, int nP, unsigned* cnt, unsigned char* lds) {
;     ...
;         asm volatile("s_waitcnt vmcnt(0)" ::: "memory");
;         __syncthreads();
;         if (threadIdx.x == 0) {
;             __builtin_amdgcn_fence(__ATOMIC_RELEASE, "agent");
;             __hip_atomic_store(cnt, (unsigned)(layer * 16 + round + 1), __ATOMIC_RELAXED, __HIP_MEMORY_SCOPE_AGENT);
;         }
.LBB0_237:
	s_or_b64 exec, exec, s[12:13]
	s_waitcnt vmcnt(0)
	s_waitcnt vmcnt(63) expcnt(7) lgkmcnt(15)
	s_barrier
	s_mov_b64 s[0:1], exec
	v_cmp_eq_u32_e32 vcc, 0x1c0, v160
	s_nop 0
	s_and_b64 s[12:13], s[0:1], vcc
	s_mov_b64 exec, s[12:13]
	s_cbranch_execz .LBB0_140
	s_add_i32 s12, s16, s20
	s_cmp_lt_u32 s12, s17
	s_cbranch_scc0 .Lpub_do
	s_sub_i32 s13, s19, 1
	s_and_b32 s13, s13, 15
	s_movk_i32 s12, 0x3ff
	s_movk_i32 s14, 0x2a
	s_cmp_eq_u32 s30, 3
	s_cselect_b32 s12, s14, s12
	s_bitcmp1_b32 s12, s13
	s_cbranch_scc0 .LBB0_140
